# attention work queue: fetch the next item index one item ahead (atomic issued at item start, consumed at next loop top)
# baseline (speedup 1.0000x reference)
; #define LAS __attribute__((address_space(3)))
;     const int tid = threadIdx.x;
;     const float lam = ((const float*)(A.ws + WS_CTL))[1];
;     unsigned* ctr = (unsigned*)(A.ws + WS_CTL) + 2 * rep;
;     LAS int* slot = (LAS int*)(lds + LDS_BYTES - 64);
;     const int nml = ((int)gridDim.x > 64) ? 32 : 1;
;     if ((int)blockIdx.x < nml) for (int bh = blockIdx.x; bh < 32; bh += nml) mlstm_state(A, lds, bh >> 2, bh & 3);
;     for (;;) {
;         if (tid == 0) slot[0] = (int)atomicAdd(ctr, 1u);
;         __syncthreads();
;         const int it = slot[0];
.LBB0_311:
	s_add_u32 s60, s50, 0x7071800
	s_addc_u32 s61, s51, 0
	s_add_i32 s33, 0, 0x23fc0
	s_waitcnt vmcnt(0)
	v_mov_b32_e32 v131, v130
	s_mov_b32 s63, 0
	v_mov_b32_e32 v139, s33
	s_movk_i32 s76, 0x1c00
	s_movk_i32 s77, 0x1000
	s_movk_i32 s78, 0x120
	s_mov_b32 s79, 0xf149f2ca
	s_mov_b32 s88, 0x3e38aa3b
	s_mov_b64 s[68:69], 0x5000400
	v_mov_b32_e32 v140, 0x358637bd
	s_mov_b32 s89, 0x800000
	s_mov_b32 s90, 0x5000000
	v_mov_b32_e32 v141, 0xe00000
	v_mov_b32_e32 v142, 0xf149f2ca
	s_and_saveexec_b64 s[4:5], s[18:19]
	s_cbranch_execz .Lqf_first_skip
	v_mov_b32_e32 v1, 1
	global_atomic_add v237, v129, v1, s[50:51] sc0
.Lqf_first_skip:
	s_or_b64 exec, exec, s[4:5]
	s_branch .LBB0_315

; #define LAS __attribute__((address_space(3)))
; __device__ __forceinline__ void attn_item(const Args& A, LAS unsigned char* lds, int b, int h, int qb, float lam) {
;     int tid_o = threadIdx.x; asm volatile("" : "+v"(tid_o)); const int tid = tid_o, lane = tid & 63, w = tid >> 6, g = lane >> 4, l15 = lane & 15;
;     const bf16_t* P = (const bf16_t*)(A.ws + WS_P);
;     bf16_t* ACT = (bf16_t*)(A.ws + WS_ACT);
;     const int t0 = qb * 128, ntiles = 2 * (qb + 1);
;     const size_t rowbase = (size_t)b * SEQ;
;     bf16x8 qf[2][2];
;     { const bf16_t* qp = P + (rowbase + t0 + 16 * w + l15) * NP + 2048 + h * 128 + 8 * g;
; #pragma unroll
;       for (int p = 0; p < 2; ++p)
; #pragma unroll
;           for (int ks = 0; ks < 2; ++ks) qf[p][ks] = *(const bf16x8*)(qp + p * 64 + ks * 32); }
;     f32x4 o[2][8];
; #pragma unroll
;     for (int p = 0; p < 2; ++p)
; #pragma unroll
;         for (int vt = 0; vt < 8; ++vt) o[p][vt] = (f32x4){0.f, 0.f, 0.f, 0.f};
;     float mrun[2] = {-1e30f, -1e30f}, lrun[2] = {0.f, 0.f};
;     const int srow = tid >> 3, sseg = tid & 7;
;     const bf16_t* kg = P + (rowbase + srow) * NP + 2560 + h * 128 + sseg * 16;
;     const bf16_t* vg = P + (rowbase + srow) * NP + 3072 + h * 128 + sseg * 16;
;     u32x4 kr0, kr1, vr0, vr1;
;     kr0 = *(const u32x4*)(kg); kr1 = *(const u32x4*)(kg + 8); vr0 = *(const u32x4*)(vg); vr1 = *(const u32x4*)(vg + 8);
;     { LAS unsigned char* kb = lds + srow * AK_STRIDE + sseg * 32; LAS unsigned char* vb = lds + 2 * AK_BYTES + srow * AV_STRIDE + sseg * 32;
;       *(LAS u32x4*)kb = kr0; *(LAS u32x4*)(kb + 16) = kr1; *(LAS u32x4*)vb = vr0; *(LAS u32x4*)(vb + 16) = vr1; }
;     __syncthreads();
;     ...
;     for (;;) {
;         if (tid == 0) slot[0] = (int)atomicAdd(ctr, 1u);
;         __syncthreads();
;         const int it = slot[0];
;         __syncthreads();
;         if (it >= 512) break;
.LBB0_315:
	s_and_saveexec_b64 s[0:1], s[18:19]
	s_cbranch_execz .LBB0_319
	s_waitcnt vmcnt(0)
	v_readfirstlane_b32 s4, v237
	v_mov_b32_e32 v1, s33
	s_nop 0
	v_mov_b32_e32 v0, s4
	ds_write_b32 v1, v0
.LBB0_319:
	s_or_b64 exec, exec, s[0:1]
	s_waitcnt lgkmcnt(0)
	s_barrier
	ds_read_b32 v0, v139
	s_movk_i32 s0, 0x1ff
	s_waitcnt lgkmcnt(0)
	s_barrier
	v_cmp_lt_i32_e32 vcc, s0, v0
	v_readfirstlane_b32 s4, v0
	s_mov_b64 s[0:1], -1
	s_cbranch_vccnz .LBB0_314
	s_and_saveexec_b64 s[6:7], s[18:19]
	s_cbranch_execz .Lqf_next_skip
	v_mov_b32_e32 v1, 1
	global_atomic_add v237, v129, v1, s[50:51] sc0
.Lqf_next_skip:
	s_or_b64 exec, exec, s[6:7]
	v_mov_b32_e32 v24, v214
	s_lshl_b32 s0, s4, 9
	s_and_b32 s5, s0, 0x3800
	s_lshl_b32 s0, s4, 7
	v_ashrrev_i32_e32 v25, 3, v24
	v_mov_b64_e32 v[16:17], s[54:55]
	s_and_b32 s91, s0, 0x180
	v_add_u32_e32 v0, s5, v25
	s_lshl_b32 s0, s91, 1
	s_mov_b32 s1, s63
	v_mad_i64_i32 v[0:1], s[6:7], v0, s76, v[16:17]
	v_lshlrev_b32_e32 v2, 5, v24
	v_lshl_add_u64 v[0:1], v[0:1], 0, s[0:1]
	v_and_b32_e32 v18, 0xe0, v2
	v_mov_b32_e32 v19, v129
	v_lshl_add_u64 v[0:1], v[0:1], 0, v[18:19]
	s_mov_b64 s[6:7], 0x1400
	v_lshl_add_u64 v[4:5], v[0:1], 0, s[6:7]
	s_mov_b64 s[6:7], 0x1800
	s_ashr_i32 s8, s4, 5
	v_lshl_add_u64 v[12:13], v[0:1], 0, s[6:7]
	s_sub_i32 s6, 15, s8
	v_ashrrev_i32_e32 v20, 2, v24
	s_lshl_b32 s9, s6, 7
	v_and_b32_e32 v20, -16, v20
	s_add_i32 s62, s9, s5
	v_ashrrev_i32_e32 v21, 31, v20
	v_and_b32_e32 v26, 15, v24
	v_lshl_add_u64 v[22:23], v[20:21], 0, s[62:63]
	v_or_b32_e32 v21, v22, v26
	v_mad_u64_u32 v[16:17], s[6:7], v21, s76, v[16:17]
	v_bfe_u32 v19, v24, 4, 2
	v_mad_i32_i24 v17, v23, s76, v17
	v_add_co_u32_e32 v8, vcc, s77, v0
	v_lshl_add_u64 v[16:17], v[16:17], 0, s[0:1]
	v_lshlrev_b32_e32 v128, 4, v19
	v_addc_co_u32_e32 v9, vcc, 0, v1, vcc
	v_lshl_add_u64 v[16:17], v[16:17], 0, v[128:129]
	s_mov_b64 s[0:1], 0x1000
	global_load_dwordx4 v[0:3], v[8:9], off offset:1024
	s_nop 0
	global_load_dwordx4 v[4:7], v[4:5], off offset:16
	s_nop 0
	global_load_dwordx4 v[8:11], v[8:9], off offset:2048
	s_nop 0
	global_load_dwordx4 v[12:15], v[12:13], off offset:16
	v_lshl_add_u64 v[22:23], v[16:17], 0, s[0:1]
	v_add_co_u32_e32 v16, vcc, s77, v16
	s_and_b32 s0, s4, 3
	s_nop 0
	v_addc_co_u32_e32 v17, vcc, 0, v17, vcc
	global_load_dwordx4 v[72:75], v[22:23], off offset:64
	global_load_dwordx4 v[68:71], v[22:23], off offset:128
	global_load_dwordx4 v[76:79], v[16:17], off
	global_load_dwordx4 v[64:67], v[22:23], off offset:192
	s_lshl_b32 s1, s8, 1
	v_lshlrev_b32_e32 v16, 3, v24
	s_bfe_u32 s6, s4, 0x30002
	s_lshl_b32 s4, s0, 8
	s_sub_i32 s93, 31, s1
	v_mul_lo_u32 v22, v25, s78
	v_lshlrev_b32_e32 v143, 2, v19
	v_and_b32_e32 v19, 24, v16
	v_mad_i64_i32 v[16:17], s[0:1], v25, s76, 0
	v_bfe_u32 v21, v24, 2, 2
	v_add3_u32 v151, 0, v22, v18
	v_mad_u64_u32 v[16:17], s[0:1], s6, v141, v[16:17]
	v_add_u32_e32 v147, s9, v20
	v_or_b32_e32 v20, v143, v21
	v_add_u32_e32 v145, 0, v19
	v_or3_b32 v16, v16, s4, v18
	v_mul_u32_u24_e32 v150, 0x120, v26
	v_or_b32_e32 v132, v147, v26
	v_mul_u32_u24_e32 v146, 0x120, v20
	v_mad_u32_u24 v154, v20, s78, v145
	v_lshl_add_u64 v[134:135], s[60:61], 0, v[16:17]
	s_mov_b32 s92, 0
	v_add3_u32 v152, 0, v150, v128
	s_mov_b32 s62, s5
	v_or_b32_e32 v153, 15, v147
	v_mov_b32_e32 v144, 0
	v_mov_b32_e32 v138, 0xf149f2ca
	s_mov_b32 s94, 63
	v_mov_b32_e32 v136, 0xf149f2ca
	v_mov_b32_e32 v133, 0
	s_waitcnt vmcnt(7)
	ds_write_b128 v151, v[0:3]
	s_waitcnt vmcnt(6)
	ds_write_b128 v151, v[4:7] offset:16
	s_waitcnt vmcnt(5)
	ds_write_b128 v151, v[8:11] offset:36864
	s_waitcnt vmcnt(4)
	ds_write_b128 v151, v[12:15] offset:36880
	v_mov_b32_e32 v12, v129
	v_mov_b32_e32 v13, v129
	v_mov_b32_e32 v14, v129
	v_mov_b32_e32 v15, v129
	v_mov_b64_e32 v[26:27], v[14:15]
	v_mov_b64_e32 v[34:35], v[14:15]
	v_mov_b64_e32 v[42:43], v[14:15]
	v_mov_b64_e32 v[50:51], v[14:15]
	v_mov_b64_e32 v[58:59], v[14:15]
	v_mov_b64_e32 v[0:1], v[12:13]
	v_mov_b64_e32 v[8:9], v[12:13]
	v_mov_b64_e32 v[22:23], v[14:15]
	v_mov_b64_e32 v[30:31], v[14:15]
	v_mov_b64_e32 v[38:39], v[14:15]
	v_mov_b64_e32 v[46:47], v[14:15]
	v_mov_b64_e32 v[54:55], v[14:15]
	v_mov_b64_e32 v[62:63], v[14:15]
	v_mov_b64_e32 v[18:19], v[14:15]
	v_mov_b64_e32 v[4:5], v[12:13]
	v_mov_b64_e32 v[24:25], v[12:13]
	v_mov_b64_e32 v[32:33], v[12:13]
	v_mov_b64_e32 v[40:41], v[12:13]
	v_mov_b64_e32 v[48:49], v[12:13]
	v_mov_b64_e32 v[56:57], v[12:13]
	v_mov_b64_e32 v[2:3], v[14:15]
	v_mov_b64_e32 v[10:11], v[14:15]
	v_mov_b64_e32 v[20:21], v[12:13]
	v_mov_b64_e32 v[28:29], v[12:13]
	v_mov_b64_e32 v[36:37], v[12:13]
	v_mov_b64_e32 v[44:45], v[12:13]
	v_mov_b64_e32 v[52:53], v[12:13]
	v_mov_b64_e32 v[60:61], v[12:13]
	v_mov_b64_e32 v[16:17], v[12:13]
	v_mov_b64_e32 v[6:7], v[14:15]
	s_waitcnt lgkmcnt(0)
	s_barrier
	s_branch .LBB0_323
